# v46 with the static raise for waves 4-7 at s_setprio 3 instead of 1
# speedup vs baseline: 1.0047x; 1.0047x over previous
; #define PG8_BAR __builtin_amdgcn_s_barrier()
;     __device__ bool next(int i, Unit& u) const { const int L = i * G + c; if (L >= 512) return false; u.pm = 0; u.pn = L; u.offA = 0; u.offB = (size_t)L * 256 * 256 * 2; return true; }
; template <class Epi, class Sched>
; __device__ __forceinline__ void gemm_phase(LAS unsigned char* lds, const Gemm g, const Sched& S, const Epi& E) {
;     ...
;         const bool has_next = S.next(ui + 1, nxt);
;         const char* nA = has_next ? (const char*)g.A + nxt.offA : cA; const char* nB = has_next ? (const char*)g.Bt + nxt.offB : cB;
;         for (int t = 0; t < nt; t += 2) {
;             const bool last = (t == nt - 2);
;             const char* a1 = cA + (size_t)(t + 1) * kstep;
;             const char* a2 = last ? nA : cA + (size_t)(t + 2) * kstep; const char* b2 = last ? nB : cB + (size_t)(t + 2) * kstep;
;             const char* a3 = a2 + kstep; const char* b3 = b2 + kstep;
;     ...
;         if (!has_next) break;
; #pragma unroll
;         for (int a = 0; a < 2; ++a)
; #pragma unroll
;             for (int b = 0; b < 2; ++b)
; #pragma unroll
;                 for (int m = 0; m < 4; ++m)
; #pragma unroll
;                     for (int n = 0; n < 2; ++n) acc[a][b][m][n] = (f32x4){0.f, 0.f, 0.f, 0.f};
;         cur = nxt; cA = nA; cB = nB; ++ui;
;         if (wr == 1) PG8_BAR;
.LBB0_220:
	s_add_u32 s50, s2, s46
	s_addc_u32 s51, s3, s47
	s_add_u32 s76, s7, s48
	s_addc_u32 s77, s11, s49
	s_andn2_b64 vcc, exec, s[74:75]
	s_cbranch_vccnz .Lzc_6242
	s_and_b64 s[8:9], s[36:37], exec
	s_cselect_b32 s10, s51, s1
	s_cselect_b32 s43, s50, s0
	s_cselect_b32 s45, s77, s39
	s_cselect_b32 vcc_lo, s76, s38
	s_add_u32 s0, s0, 0x40080
	s_addc_u32 s1, s1, 0
	s_add_u32 vcc_hi, s38, 0x100
	v_mov_b32_e32 v6, 0
	s_mov_b64 s[22:23], s[74:75]
	s_addc_u32 s8, s39, 0
	s_mov_b32 s9, 0
	v_mov_b32_e32 v7, v6
	v_mov_b32_e32 v8, v6
	v_mov_b32_e32 v9, v6
	v_mov_b32_e32 v14, v6
	v_mov_b32_e32 v15, v6
	v_mov_b32_e32 v16, v6
	v_mov_b32_e32 v17, v6
	v_mov_b32_e32 v22, v6
	v_mov_b32_e32 v23, v6
	v_mov_b32_e32 v24, v6
	v_mov_b32_e32 v25, v6
	v_mov_b32_e32 v30, v6
	v_mov_b32_e32 v31, v6
	v_mov_b32_e32 v32, v6
	v_mov_b32_e32 v33, v6
	v_mov_b32_e32 v38, v6
	v_mov_b32_e32 v39, v6
	v_mov_b32_e32 v40, v6
	v_mov_b32_e32 v41, v6
	v_mov_b32_e32 v46, v6
	v_mov_b32_e32 v47, v6
	v_mov_b32_e32 v48, v6
	v_mov_b32_e32 v49, v6
	v_mov_b32_e32 v54, v6
	v_mov_b32_e32 v55, v6
	v_mov_b32_e32 v56, v6
	v_mov_b32_e32 v57, v6
	v_mov_b32_e32 v62, v6
	v_mov_b32_e32 v63, v6
	v_mov_b32_e32 v64, v6
	v_mov_b32_e32 v65, v6
	v_mov_b32_e32 v2, v6
	v_mov_b32_e32 v3, v6
	v_mov_b32_e32 v4, v6
	v_mov_b32_e32 v5, v6
	v_mov_b32_e32 v10, v6
	v_mov_b32_e32 v11, v6
	v_mov_b32_e32 v12, v6
	v_mov_b32_e32 v13, v6
	v_mov_b32_e32 v18, v6
	v_mov_b32_e32 v19, v6
	v_mov_b32_e32 v20, v6
	v_mov_b32_e32 v21, v6
	v_mov_b32_e32 v26, v6
	v_mov_b32_e32 v27, v6
	v_mov_b32_e32 v28, v6
	v_mov_b32_e32 v29, v6
	v_mov_b32_e32 v34, v6
	v_mov_b32_e32 v35, v6
	v_mov_b32_e32 v36, v6
	v_mov_b32_e32 v37, v6
	v_mov_b32_e32 v42, v6
	v_mov_b32_e32 v43, v6
	v_mov_b32_e32 v44, v6
	v_mov_b32_e32 v45, v6
	v_mov_b32_e32 v50, v6
	v_mov_b32_e32 v51, v6
	v_mov_b32_e32 v52, v6
	v_mov_b32_e32 v53, v6
	v_mov_b32_e32 v58, v6
	v_mov_b32_e32 v59, v6
	v_mov_b32_e32 v60, v6
	v_mov_b32_e32 v61, v6
	v_mov_b32_e32 v70, v6
	v_mov_b32_e32 v71, v6
	v_mov_b32_e32 v72, v6
	v_mov_b32_e32 v73, v6
	v_mov_b32_e32 v78, v6
	v_mov_b32_e32 v79, v6
	v_mov_b32_e32 v80, v6
	v_mov_b32_e32 v81, v6
	v_mov_b32_e32 v86, v6
	v_mov_b32_e32 v87, v6
	v_mov_b32_e32 v88, v6
	v_mov_b32_e32 v89, v6
	v_mov_b32_e32 v94, v6
	v_mov_b32_e32 v95, v6
	v_mov_b32_e32 v96, v6
	v_mov_b32_e32 v97, v6
	v_mov_b32_e32 v102, v6
	v_mov_b32_e32 v103, v6
	v_mov_b32_e32 v104, v6
	v_mov_b32_e32 v105, v6
	v_mov_b32_e32 v110, v6
	v_mov_b32_e32 v111, v6
	v_mov_b32_e32 v112, v6
	v_mov_b32_e32 v113, v6
	v_mov_b32_e32 v118, v6
	v_mov_b32_e32 v119, v6
	v_mov_b32_e32 v120, v6
	v_mov_b32_e32 v121, v6
	v_mov_b32_e32 v126, v6
	v_mov_b32_e32 v127, v6
	v_mov_b32_e32 v128, v6
	v_mov_b32_e32 v129, v6
	v_mov_b32_e32 v66, v6
	v_mov_b32_e32 v67, v6
	v_mov_b32_e32 v68, v6
	v_mov_b32_e32 v69, v6
	v_mov_b32_e32 v74, v6
	v_mov_b32_e32 v75, v6
	v_mov_b32_e32 v76, v6
	v_mov_b32_e32 v77, v6
	v_mov_b32_e32 v82, v6
	v_mov_b32_e32 v83, v6
	v_mov_b32_e32 v84, v6
	v_mov_b32_e32 v85, v6
	v_mov_b32_e32 v90, v6
	v_mov_b32_e32 v91, v6
	v_mov_b32_e32 v92, v6
	v_mov_b32_e32 v93, v6
	v_mov_b32_e32 v98, v6
	v_mov_b32_e32 v99, v6
	v_mov_b32_e32 v100, v6
	v_mov_b32_e32 v101, v6
	v_mov_b32_e32 v106, v6
	v_mov_b32_e32 v107, v6
	v_mov_b32_e32 v108, v6
	v_mov_b32_e32 v109, v6
	v_mov_b32_e32 v114, v6
	v_mov_b32_e32 v115, v6
	v_mov_b32_e32 v116, v6
	v_mov_b32_e32 v117, v6
	v_mov_b32_e32 v122, v6
	v_mov_b32_e32 v123, v6
	v_mov_b32_e32 v124, v6
	v_mov_b32_e32 v125, v6
	v_readfirstlane_b32 s96, v193
	s_lshr_b32 s96, s96, 8
	s_cmp_eq_u32 s96, 1
	s_cbranch_scc0 .Lnp_222
	s_setprio 3

; #define PG8_BAR __builtin_amdgcn_s_barrier()
;     __device__ bool next(int i, Unit& u) const { const int L = i * G + c; if (L >= 512) return false; u.pm = 0; u.pn = L; u.offA = 0; u.offB = (size_t)L * 256 * 256 * 2; return true; }
; template <class Epi, class Sched>
; __device__ __forceinline__ void gemm_phase(LAS unsigned char* lds, const Gemm g, const Sched& S, const Epi& E) {
;     ...
;         const bool has_next = S.next(ui + 1, nxt);
;         const char* nA = has_next ? (const char*)g.A + nxt.offA : cA; const char* nB = has_next ? (const char*)g.Bt + nxt.offB : cB;
;         for (int t = 0; t < nt; t += 2) {
;             const bool last = (t == nt - 2);
;             const char* a1 = cA + (size_t)(t + 1) * kstep;
;             const char* a2 = last ? nA : cA + (size_t)(t + 2) * kstep; const char* b2 = last ? nB : cB + (size_t)(t + 2) * kstep;
;             const char* a3 = a2 + kstep; const char* b3 = b2 + kstep;
;     ...
;         if (!has_next) break;
; #pragma unroll
;         for (int a = 0; a < 2; ++a)
; #pragma unroll
;             for (int b = 0; b < 2; ++b)
; #pragma unroll
;                 for (int m = 0; m < 4; ++m)
; #pragma unroll
;                     for (int n = 0; n < 2; ++n) acc[a][b][m][n] = (f32x4){0.f, 0.f, 0.f, 0.f};
;         cur = nxt; cA = nA; cB = nB; ++ui;
;         if (wr == 1) PG8_BAR;
.LBB0_296:
	s_add_u32 s76, s66, s50
	s_addc_u32 s77, s67, s51
	v_readlane_b32 s22, v250, 44
	s_add_u32 s34, s73, s0
	v_readlane_b32 s23, v250, 45
	s_addc_u32 s35, s74, s1
	s_andn2_b64 vcc, exec, s[22:23]
	s_cbranch_vccnz .Lzc_8429
	s_and_b64 s[38:39], s[36:37], exec
	s_mov_b32 s22, s73
	s_cselect_b32 s43, s77, s9
	s_cselect_b32 s73, s76, s8
	s_cselect_b32 s82, s35, s21
	s_cselect_b32 s83, s34, s20
	s_add_u32 s84, s20, 0x100
	v_mov_b32_e32 v2, 0
	s_mov_b32 vcc_lo, s75
	s_mov_b32 s23, s74
	s_addc_u32 s85, s21, 0
	s_mov_b32 s38, 0
	s_waitcnt lgkmcnt(0)
	v_mov_b32_e32 v3, v2
	v_mov_b32_e32 v4, v2
	v_mov_b32_e32 v5, v2
	v_mov_b32_e32 v6, v2
	v_mov_b32_e32 v7, v2
	v_mov_b32_e32 v8, v2
	v_mov_b32_e32 v9, v2
	v_mov_b32_e32 v10, v2
	v_mov_b32_e32 v11, v2
	v_mov_b32_e32 v12, v2
	v_mov_b32_e32 v13, v2
	v_mov_b32_e32 v14, v2
	v_mov_b32_e32 v15, v2
	v_mov_b32_e32 v16, v2
	v_mov_b32_e32 v17, v2
	v_mov_b32_e32 v22, v2
	v_mov_b32_e32 v23, v2
	v_mov_b32_e32 v24, v2
	v_mov_b32_e32 v25, v2
	v_mov_b32_e32 v30, v2
	v_mov_b32_e32 v31, v2
	v_mov_b32_e32 v32, v2
	v_mov_b32_e32 v33, v2
	v_mov_b32_e32 v38, v2
	v_mov_b32_e32 v39, v2
	v_mov_b32_e32 v40, v2
	v_mov_b32_e32 v41, v2
	v_mov_b32_e32 v46, v2
	v_mov_b32_e32 v47, v2
	v_mov_b32_e32 v48, v2
	v_mov_b32_e32 v49, v2
	v_mov_b32_e32 v18, v2
	v_mov_b32_e32 v19, v2
	v_mov_b32_e32 v20, v2
	v_mov_b32_e32 v21, v2
	v_mov_b32_e32 v26, v2
	v_mov_b32_e32 v27, v2
	v_mov_b32_e32 v28, v2
	v_mov_b32_e32 v29, v2
	v_mov_b32_e32 v34, v2
	v_mov_b32_e32 v35, v2
	v_mov_b32_e32 v36, v2
	v_mov_b32_e32 v37, v2
	v_mov_b32_e32 v42, v2
	v_mov_b32_e32 v43, v2
	v_mov_b32_e32 v44, v2
	v_mov_b32_e32 v45, v2
	v_mov_b32_e32 v50, v2
	v_mov_b32_e32 v51, v2
	v_mov_b32_e32 v52, v2
	v_mov_b32_e32 v53, v2
	v_mov_b32_e32 v54, v2
	v_mov_b32_e32 v55, v2
	v_mov_b32_e32 v56, v2
	v_mov_b32_e32 v57, v2
	v_mov_b32_e32 v58, v2
	v_mov_b32_e32 v59, v2
	v_mov_b32_e32 v60, v2
	v_mov_b32_e32 v61, v2
	v_mov_b32_e32 v62, v2
	v_mov_b32_e32 v63, v2
	v_mov_b32_e32 v64, v2
	v_mov_b32_e32 v65, v2
	v_mov_b32_e32 v66, v2
	v_mov_b32_e32 v67, v2
	v_mov_b32_e32 v68, v2
	v_mov_b32_e32 v69, v2
	v_mov_b32_e32 v70, v2
	v_mov_b32_e32 v71, v2
	v_mov_b32_e32 v72, v2
	v_mov_b32_e32 v73, v2
	v_mov_b32_e32 v74, v2
	v_mov_b32_e32 v75, v2
	v_mov_b32_e32 v76, v2
	v_mov_b32_e32 v77, v2
	v_mov_b32_e32 v78, v2
	v_mov_b32_e32 v79, v2
	v_mov_b32_e32 v80, v2
	v_mov_b32_e32 v81, v2
	v_mov_b32_e32 v86, v2
	v_mov_b32_e32 v87, v2
	v_mov_b32_e32 v88, v2
	v_mov_b32_e32 v89, v2
	v_mov_b32_e32 v94, v2
	v_mov_b32_e32 v95, v2
	v_mov_b32_e32 v96, v2
	v_mov_b32_e32 v97, v2
	v_mov_b32_e32 v102, v2
	v_mov_b32_e32 v103, v2
	v_mov_b32_e32 v104, v2
	v_mov_b32_e32 v105, v2
	v_mov_b32_e32 v110, v2
	v_mov_b32_e32 v111, v2
	v_mov_b32_e32 v112, v2
	v_mov_b32_e32 v113, v2
	v_mov_b32_e32 v82, v2
	v_mov_b32_e32 v83, v2
	v_mov_b32_e32 v84, v2
	v_mov_b32_e32 v85, v2
	v_mov_b32_e32 v90, v2
	v_mov_b32_e32 v91, v2
	v_mov_b32_e32 v92, v2
	v_mov_b32_e32 v93, v2
	v_mov_b32_e32 v98, v2
	v_mov_b32_e32 v99, v2
	v_mov_b32_e32 v100, v2
	v_mov_b32_e32 v101, v2
	v_mov_b32_e32 v106, v2
	v_mov_b32_e32 v107, v2
	v_mov_b32_e32 v108, v2
	v_mov_b32_e32 v109, v2
	v_mov_b32_e32 v114, v2
	v_mov_b32_e32 v115, v2
	v_mov_b32_e32 v116, v2
	v_mov_b32_e32 v117, v2
	v_mov_b32_e32 v118, v2
	v_mov_b32_e32 v119, v2
	v_mov_b32_e32 v120, v2
	v_mov_b32_e32 v121, v2
	v_mov_b32_e32 v122, v2
	v_mov_b32_e32 v123, v2
	v_mov_b32_e32 v124, v2
	v_mov_b32_e32 v125, v2
	v_mov_b32_e32 v126, v2
	v_mov_b32_e32 v127, v2
	v_mov_b32_e32 v128, v2
	v_mov_b32_e32 v129, v2
	v_readfirstlane_b32 s96, v193
	s_lshr_b32 s96, s96, 8
	s_cmp_eq_u32 s96, 1
	s_cbranch_scc0 .Lnp_298
	s_setprio 3

; #define PG8_BAR __builtin_amdgcn_s_barrier()
;     __device__ bool next(int i, Unit& u) const { const int L = i * G + c; if (L >= 512) return false; u.pm = 0; u.pn = L; u.offA = 0; u.offB = (size_t)L * 256 * 256 * 2; return true; }
; template <class Epi, class Sched>
; __device__ __forceinline__ void gemm_phase(LAS unsigned char* lds, const Gemm g, const Sched& S, const Epi& E) {
;     ...
;         const bool has_next = S.next(ui + 1, nxt);
;         const char* nA = has_next ? (const char*)g.A + nxt.offA : cA; const char* nB = has_next ? (const char*)g.Bt + nxt.offB : cB;
;         for (int t = 0; t < nt; t += 2) {
;             const bool last = (t == nt - 2);
;             const char* a1 = cA + (size_t)(t + 1) * kstep;
;             const char* a2 = last ? nA : cA + (size_t)(t + 2) * kstep; const char* b2 = last ? nB : cB + (size_t)(t + 2) * kstep;
;             const char* a3 = a2 + kstep; const char* b3 = b2 + kstep;
;     ...
;         if (!has_next) break;
; #pragma unroll
;         for (int a = 0; a < 2; ++a)
; #pragma unroll
;             for (int b = 0; b < 2; ++b)
; #pragma unroll
;                 for (int m = 0; m < 4; ++m)
; #pragma unroll
;                     for (int n = 0; n < 2; ++n) acc[a][b][m][n] = (f32x4){0.f, 0.f, 0.f, 0.f};
;         cur = nxt; cA = nA; cB = nB; ++ui;
;         if (wr == 1) PG8_BAR;
.LBB0_483:
	s_add_u32 s76, s2, s50
	s_addc_u32 s77, s3, s51
	v_readlane_b32 s8, v254, 4
	v_readlane_b32 s9, v254, 5
	s_add_u32 s8, s8, s36
	s_addc_u32 s9, s9, s37
	s_andn2_b64 vcc, exec, s[34:35]
	s_cbranch_vccnz .Lzc_11212
	s_and_b64 s[42:43], s[20:21], exec
	s_cselect_b32 s47, s77, s39
	s_cselect_b32 s49, s76, s38
	s_cselect_b32 s73, s9, s41
	s_cselect_b32 s82, s8, s40
	s_add_u32 s38, s38, 0x40080
	s_addc_u32 s39, s39, 0
	s_add_u32 s83, s40, 0x100
	v_mov_b32_e32 v6, 0
	s_addc_u32 s84, s41, 0
	s_mov_b32 s40, 0
	v_mov_b32_e32 v7, v6
	v_mov_b32_e32 v8, v6
	v_mov_b32_e32 v9, v6
	v_mov_b32_e32 v14, v6
	v_mov_b32_e32 v15, v6
	v_mov_b32_e32 v16, v6
	v_mov_b32_e32 v17, v6
	v_mov_b32_e32 v22, v6
	v_mov_b32_e32 v23, v6
	v_mov_b32_e32 v24, v6
	v_mov_b32_e32 v25, v6
	v_mov_b32_e32 v26, v6
	v_mov_b32_e32 v27, v6
	v_mov_b32_e32 v28, v6
	v_mov_b32_e32 v29, v6
	v_mov_b32_e32 v38, v6
	v_mov_b32_e32 v39, v6
	v_mov_b32_e32 v40, v6
	v_mov_b32_e32 v41, v6
	v_mov_b32_e32 v42, v6
	v_mov_b32_e32 v43, v6
	v_mov_b32_e32 v44, v6
	v_mov_b32_e32 v45, v6
	v_mov_b32_e32 v54, v6
	v_mov_b32_e32 v55, v6
	v_mov_b32_e32 v56, v6
	v_mov_b32_e32 v57, v6
	v_mov_b32_e32 v58, v6
	v_mov_b32_e32 v59, v6
	v_mov_b32_e32 v60, v6
	v_mov_b32_e32 v61, v6
	v_mov_b32_e32 v2, v6
	v_mov_b32_e32 v3, v6
	v_mov_b32_e32 v4, v6
	v_mov_b32_e32 v5, v6
	v_mov_b32_e32 v10, v6
	v_mov_b32_e32 v11, v6
	v_mov_b32_e32 v12, v6
	v_mov_b32_e32 v13, v6
	v_mov_b32_e32 v18, v6
	v_mov_b32_e32 v19, v6
	v_mov_b32_e32 v20, v6
	v_mov_b32_e32 v21, v6
	v_mov_b32_e32 v30, v6
	v_mov_b32_e32 v31, v6
	v_mov_b32_e32 v32, v6
	v_mov_b32_e32 v33, v6
	v_mov_b32_e32 v34, v6
	v_mov_b32_e32 v35, v6
	v_mov_b32_e32 v36, v6
	v_mov_b32_e32 v37, v6
	v_mov_b32_e32 v46, v6
	v_mov_b32_e32 v47, v6
	v_mov_b32_e32 v48, v6
	v_mov_b32_e32 v49, v6
	v_mov_b32_e32 v50, v6
	v_mov_b32_e32 v51, v6
	v_mov_b32_e32 v52, v6
	v_mov_b32_e32 v53, v6
	v_mov_b32_e32 v62, v6
	v_mov_b32_e32 v63, v6
	v_mov_b32_e32 v64, v6
	v_mov_b32_e32 v65, v6
	v_mov_b32_e32 v70, v6
	v_mov_b32_e32 v71, v6
	v_mov_b32_e32 v72, v6
	v_mov_b32_e32 v73, v6
	v_mov_b32_e32 v74, v6
	v_mov_b32_e32 v75, v6
	v_mov_b32_e32 v76, v6
	v_mov_b32_e32 v77, v6
	v_mov_b32_e32 v86, v6
	v_mov_b32_e32 v87, v6
	v_mov_b32_e32 v88, v6
	v_mov_b32_e32 v89, v6
	v_mov_b32_e32 v90, v6
	v_mov_b32_e32 v91, v6
	v_mov_b32_e32 v92, v6
	v_mov_b32_e32 v93, v6
	v_mov_b32_e32 v102, v6
	v_mov_b32_e32 v103, v6
	v_mov_b32_e32 v104, v6
	v_mov_b32_e32 v105, v6
	v_mov_b32_e32 v106, v6
	v_mov_b32_e32 v107, v6
	v_mov_b32_e32 v108, v6
	v_mov_b32_e32 v109, v6
	v_mov_b32_e32 v118, v6
	v_mov_b32_e32 v119, v6
	v_mov_b32_e32 v120, v6
	v_mov_b32_e32 v121, v6
	v_mov_b32_e32 v126, v6
	v_mov_b32_e32 v127, v6
	v_mov_b32_e32 v128, v6
	v_mov_b32_e32 v129, v6
	v_mov_b32_e32 v66, v6
	v_mov_b32_e32 v67, v6
	v_mov_b32_e32 v68, v6
	v_mov_b32_e32 v69, v6
	v_mov_b32_e32 v78, v6
	v_mov_b32_e32 v79, v6
	v_mov_b32_e32 v80, v6
	v_mov_b32_e32 v81, v6
	v_mov_b32_e32 v82, v6
	v_mov_b32_e32 v83, v6
	v_mov_b32_e32 v84, v6
	v_mov_b32_e32 v85, v6
	v_mov_b32_e32 v94, v6
	v_mov_b32_e32 v95, v6
	v_mov_b32_e32 v96, v6
	v_mov_b32_e32 v97, v6
	v_mov_b32_e32 v98, v6
	v_mov_b32_e32 v99, v6
	v_mov_b32_e32 v100, v6
	v_mov_b32_e32 v101, v6
	v_mov_b32_e32 v110, v6
	v_mov_b32_e32 v111, v6
	v_mov_b32_e32 v112, v6
	v_mov_b32_e32 v113, v6
	v_mov_b32_e32 v114, v6
	v_mov_b32_e32 v115, v6
	v_mov_b32_e32 v116, v6
	v_mov_b32_e32 v117, v6
	v_mov_b32_e32 v122, v6
	v_mov_b32_e32 v123, v6
	v_mov_b32_e32 v124, v6
	v_mov_b32_e32 v125, v6
	v_readfirstlane_b32 s85, v193
	s_lshr_b32 s85, s85, 8
	s_cmp_eq_u32 s85, 1
	s_cbranch_scc0 .Lnp_485
	s_setprio 3

; #define PG8_BAR __builtin_amdgcn_s_barrier()
;     __device__ bool next(int i, Unit& u) const { const int L = i * G + c; if (L >= 512) return false; u.pm = 0; u.pn = L; u.offA = 0; u.offB = (size_t)L * 256 * 256 * 2; return true; }
; template <class Epi, class Sched>
; __device__ __forceinline__ void gemm_phase(LAS unsigned char* lds, const Gemm g, const Sched& S, const Epi& E) {
;     ...
;         const bool has_next = S.next(ui + 1, nxt);
;         const char* nA = has_next ? (const char*)g.A + nxt.offA : cA; const char* nB = has_next ? (const char*)g.Bt + nxt.offB : cB;
;         for (int t = 0; t < nt; t += 2) {
;             const bool last = (t == nt - 2);
;             const char* a1 = cA + (size_t)(t + 1) * kstep;
;             const char* a2 = last ? nA : cA + (size_t)(t + 2) * kstep; const char* b2 = last ? nB : cB + (size_t)(t + 2) * kstep;
;             const char* a3 = a2 + kstep; const char* b3 = b2 + kstep;
;     ...
;         if (!has_next) break;
; #pragma unroll
;         for (int a = 0; a < 2; ++a)
; #pragma unroll
;             for (int b = 0; b < 2; ++b)
; #pragma unroll
;                 for (int m = 0; m < 4; ++m)
; #pragma unroll
;                     for (int n = 0; n < 2; ++n) acc[a][b][m][n] = (f32x4){0.f, 0.f, 0.f, 0.f};
;         cur = nxt; cA = nA; cB = nB; ++ui;
;         if (wr == 1) PG8_BAR;
.LBB0_534:
	v_readlane_b32 s22, v251, 29
	v_readlane_b32 s23, v251, 30
	s_add_u32 s40, s22, s34
	s_addc_u32 s41, s23, s35
	s_add_u32 s42, s2, s36
	s_addc_u32 s43, s3, s37
	s_andn2_b64 vcc, exec, s[8:9]
	s_cbranch_vccnz .Lzc_13474
	s_and_b64 s[76:77], s[38:39], exec
	s_cselect_b32 s73, s41, s45
	s_cselect_b32 s76, s40, s44
	s_cselect_b32 s77, s43, s47
	s_cselect_b32 s78, s42, s46
	s_add_u32 s44, s44, 0x40080
	s_addc_u32 s45, s45, 0
	s_add_u32 s80, s46, 0x100
	v_mov_b32_e32 v2, 0
	s_addc_u32 s82, s47, 0
	s_mov_b32 s46, 0
	v_mov_b32_e32 v3, v2
	v_mov_b32_e32 v4, v2
	v_mov_b32_e32 v5, v2
	v_mov_b32_e32 v6, v2
	v_mov_b32_e32 v7, v2
	v_mov_b32_e32 v8, v2
	v_mov_b32_e32 v9, v2
	v_mov_b32_e32 v18, v2
	v_mov_b32_e32 v19, v2
	v_mov_b32_e32 v20, v2
	v_mov_b32_e32 v21, v2
	v_mov_b32_e32 v22, v2
	v_mov_b32_e32 v23, v2
	v_mov_b32_e32 v24, v2
	v_mov_b32_e32 v25, v2
	v_mov_b32_e32 v34, v2
	v_mov_b32_e32 v35, v2
	v_mov_b32_e32 v36, v2
	v_mov_b32_e32 v37, v2
	v_mov_b32_e32 v38, v2
	v_mov_b32_e32 v39, v2
	v_mov_b32_e32 v40, v2
	v_mov_b32_e32 v41, v2
	v_mov_b32_e32 v50, v2
	v_mov_b32_e32 v51, v2
	v_mov_b32_e32 v52, v2
	v_mov_b32_e32 v53, v2
	v_mov_b32_e32 v54, v2
	v_mov_b32_e32 v55, v2
	v_mov_b32_e32 v56, v2
	v_mov_b32_e32 v57, v2
	v_mov_b32_e32 v10, v2
	v_mov_b32_e32 v11, v2
	v_mov_b32_e32 v12, v2
	v_mov_b32_e32 v13, v2
	v_mov_b32_e32 v14, v2
	v_mov_b32_e32 v15, v2
	v_mov_b32_e32 v16, v2
	v_mov_b32_e32 v17, v2
	v_mov_b32_e32 v26, v2
	v_mov_b32_e32 v27, v2
	v_mov_b32_e32 v28, v2
	v_mov_b32_e32 v29, v2
	v_mov_b32_e32 v30, v2
	v_mov_b32_e32 v31, v2
	v_mov_b32_e32 v32, v2
	v_mov_b32_e32 v33, v2
	v_mov_b32_e32 v42, v2
	v_mov_b32_e32 v43, v2
	v_mov_b32_e32 v44, v2
	v_mov_b32_e32 v45, v2
	v_mov_b32_e32 v46, v2
	v_mov_b32_e32 v47, v2
	v_mov_b32_e32 v48, v2
	v_mov_b32_e32 v49, v2
	v_mov_b32_e32 v58, v2
	v_mov_b32_e32 v59, v2
	v_mov_b32_e32 v60, v2
	v_mov_b32_e32 v61, v2
	v_mov_b32_e32 v62, v2
	v_mov_b32_e32 v63, v2
	v_mov_b32_e32 v64, v2
	v_mov_b32_e32 v65, v2
	v_mov_b32_e32 v66, v2
	v_mov_b32_e32 v67, v2
	v_mov_b32_e32 v68, v2
	v_mov_b32_e32 v69, v2
	v_mov_b32_e32 v70, v2
	v_mov_b32_e32 v71, v2
	v_mov_b32_e32 v72, v2
	v_mov_b32_e32 v73, v2
	v_mov_b32_e32 v82, v2
	v_mov_b32_e32 v83, v2
	v_mov_b32_e32 v84, v2
	v_mov_b32_e32 v85, v2
	v_mov_b32_e32 v86, v2
	v_mov_b32_e32 v87, v2
	v_mov_b32_e32 v88, v2
	v_mov_b32_e32 v89, v2
	v_mov_b32_e32 v98, v2
	v_mov_b32_e32 v99, v2
	v_mov_b32_e32 v100, v2
	v_mov_b32_e32 v101, v2
	v_mov_b32_e32 v102, v2
	v_mov_b32_e32 v103, v2
	v_mov_b32_e32 v104, v2
	v_mov_b32_e32 v105, v2
	v_mov_b32_e32 v114, v2
	v_mov_b32_e32 v115, v2
	v_mov_b32_e32 v116, v2
	v_mov_b32_e32 v117, v2
	v_mov_b32_e32 v118, v2
	v_mov_b32_e32 v119, v2
	v_mov_b32_e32 v120, v2
	v_mov_b32_e32 v121, v2
	v_mov_b32_e32 v74, v2
	v_mov_b32_e32 v75, v2
	v_mov_b32_e32 v76, v2
	v_mov_b32_e32 v77, v2
	v_mov_b32_e32 v78, v2
	v_mov_b32_e32 v79, v2
	v_mov_b32_e32 v80, v2
	v_mov_b32_e32 v81, v2
	v_mov_b32_e32 v90, v2
	v_mov_b32_e32 v91, v2
	v_mov_b32_e32 v92, v2
	v_mov_b32_e32 v93, v2
	v_mov_b32_e32 v94, v2
	v_mov_b32_e32 v95, v2
	v_mov_b32_e32 v96, v2
	v_mov_b32_e32 v97, v2
	v_mov_b32_e32 v106, v2
	v_mov_b32_e32 v107, v2
	v_mov_b32_e32 v108, v2
	v_mov_b32_e32 v109, v2
	v_mov_b32_e32 v110, v2
	v_mov_b32_e32 v111, v2
	v_mov_b32_e32 v112, v2
	v_mov_b32_e32 v113, v2
	v_mov_b32_e32 v126, v2
	v_mov_b32_e32 v127, v2
	v_mov_b32_e32 v128, v2
	v_mov_b32_e32 v129, v2
	v_mov_b32_e32 v122, v2
	v_mov_b32_e32 v123, v2
	v_mov_b32_e32 v124, v2
	v_mov_b32_e32 v125, v2
	s_mov_b64 s[22:23], 0x800
	s_mov_b64 vcc, 0x880
	v_readfirstlane_b32 s83, v193
	s_lshr_b32 s83, s83, 8
	s_cmp_eq_u32 s83, 1
	s_cbranch_scc0 .Lnp_536
	s_setprio 3

; #define PG8_BAR __builtin_amdgcn_s_barrier()
;     __device__ bool next(int i, Unit& u) const { const int L = i * G + c; if (L >= 512) return false; u.pm = 0; u.pn = L; u.offA = 0; u.offB = (size_t)L * 256 * 256 * 2; return true; }
; template <class Epi, class Sched>
; __device__ __forceinline__ void gemm_phase(LAS unsigned char* lds, const Gemm g, const Sched& S, const Epi& E) {
;     ...
;         const bool has_next = S.next(ui + 1, nxt);
;         const char* nA = has_next ? (const char*)g.A + nxt.offA : cA; const char* nB = has_next ? (const char*)g.Bt + nxt.offB : cB;
;         for (int t = 0; t < nt; t += 2) {
;             const bool last = (t == nt - 2);
;             const char* a1 = cA + (size_t)(t + 1) * kstep;
;             const char* a2 = last ? nA : cA + (size_t)(t + 2) * kstep; const char* b2 = last ? nB : cB + (size_t)(t + 2) * kstep;
;             const char* a3 = a2 + kstep; const char* b3 = b2 + kstep;
;     ...
;         if (!has_next) break;
; #pragma unroll
;         for (int a = 0; a < 2; ++a)
; #pragma unroll
;             for (int b = 0; b < 2; ++b)
; #pragma unroll
;                 for (int m = 0; m < 4; ++m)
; #pragma unroll
;                     for (int n = 0; n < 2; ++n) acc[a][b][m][n] = (f32x4){0.f, 0.f, 0.f, 0.f};
;         cur = nxt; cA = nA; cB = nB; ++ui;
;         if (wr == 1) PG8_BAR;
.LBB0_635:
	s_add_u32 s38, s68, s36
	s_addc_u32 s39, s69, s37
	s_andn2_b64 vcc, exec, s[20:21]
	s_cbranch_vccnz .Lzc_17144
	s_and_b64 s[0:1], s[40:41], exec
	s_cselect_b32 s73, s39, s43
	s_cselect_b32 s76, s38, s42
	s_add_u32 s77, s42, 0x100
	v_mov_b32_e32 v2, 0
	s_addc_u32 s78, s43, 0
	s_mov_b32 s46, 0
	s_mov_b64 s[42:43], 0
	v_mov_b32_e32 v3, v2
	v_mov_b32_e32 v4, v2
	v_mov_b32_e32 v5, v2
	v_mov_b32_e32 v10, v2
	v_mov_b32_e32 v11, v2
	v_mov_b32_e32 v12, v2
	v_mov_b32_e32 v13, v2
	v_mov_b32_e32 v34, v2
	v_mov_b32_e32 v35, v2
	v_mov_b32_e32 v36, v2
	v_mov_b32_e32 v37, v2
	v_mov_b32_e32 v42, v2
	v_mov_b32_e32 v43, v2
	v_mov_b32_e32 v44, v2
	v_mov_b32_e32 v45, v2
	v_mov_b32_e32 v66, v2
	v_mov_b32_e32 v67, v2
	v_mov_b32_e32 v68, v2
	v_mov_b32_e32 v69, v2
	v_mov_b32_e32 v74, v2
	v_mov_b32_e32 v75, v2
	v_mov_b32_e32 v76, v2
	v_mov_b32_e32 v77, v2
	v_mov_b32_e32 v98, v2
	v_mov_b32_e32 v99, v2
	v_mov_b32_e32 v100, v2
	v_mov_b32_e32 v101, v2
	v_mov_b32_e32 v106, v2
	v_mov_b32_e32 v107, v2
	v_mov_b32_e32 v108, v2
	v_mov_b32_e32 v109, v2
	v_mov_b32_e32 v18, v2
	v_mov_b32_e32 v19, v2
	v_mov_b32_e32 v20, v2
	v_mov_b32_e32 v21, v2
	v_mov_b32_e32 v26, v2
	v_mov_b32_e32 v27, v2
	v_mov_b32_e32 v28, v2
	v_mov_b32_e32 v29, v2
	v_mov_b32_e32 v50, v2
	v_mov_b32_e32 v51, v2
	v_mov_b32_e32 v52, v2
	v_mov_b32_e32 v53, v2
	v_mov_b32_e32 v58, v2
	v_mov_b32_e32 v59, v2
	v_mov_b32_e32 v60, v2
	v_mov_b32_e32 v61, v2
	v_mov_b32_e32 v82, v2
	v_mov_b32_e32 v83, v2
	v_mov_b32_e32 v84, v2
	v_mov_b32_e32 v85, v2
	v_mov_b32_e32 v90, v2
	v_mov_b32_e32 v91, v2
	v_mov_b32_e32 v92, v2
	v_mov_b32_e32 v93, v2
	v_mov_b32_e32 v114, v2
	v_mov_b32_e32 v115, v2
	v_mov_b32_e32 v116, v2
	v_mov_b32_e32 v117, v2
	v_mov_b32_e32 v122, v2
	v_mov_b32_e32 v123, v2
	v_mov_b32_e32 v124, v2
	v_mov_b32_e32 v125, v2
	v_mov_b32_e32 v6, v2
	v_mov_b32_e32 v7, v2
	v_mov_b32_e32 v8, v2
	v_mov_b32_e32 v9, v2
	v_mov_b32_e32 v14, v2
	v_mov_b32_e32 v15, v2
	v_mov_b32_e32 v16, v2
	v_mov_b32_e32 v17, v2
	v_mov_b32_e32 v38, v2
	v_mov_b32_e32 v39, v2
	v_mov_b32_e32 v40, v2
	v_mov_b32_e32 v41, v2
	v_mov_b32_e32 v46, v2
	v_mov_b32_e32 v47, v2
	v_mov_b32_e32 v48, v2
	v_mov_b32_e32 v49, v2
	v_mov_b32_e32 v70, v2
	v_mov_b32_e32 v71, v2
	v_mov_b32_e32 v72, v2
	v_mov_b32_e32 v73, v2
	v_mov_b32_e32 v78, v2
	v_mov_b32_e32 v79, v2
	v_mov_b32_e32 v80, v2
	v_mov_b32_e32 v81, v2
	v_mov_b32_e32 v102, v2
	v_mov_b32_e32 v103, v2
	v_mov_b32_e32 v104, v2
	v_mov_b32_e32 v105, v2
	v_mov_b32_e32 v110, v2
	v_mov_b32_e32 v111, v2
	v_mov_b32_e32 v112, v2
	v_mov_b32_e32 v113, v2
	v_mov_b32_e32 v22, v2
	v_mov_b32_e32 v23, v2
	v_mov_b32_e32 v24, v2
	v_mov_b32_e32 v25, v2
	v_mov_b32_e32 v30, v2
	v_mov_b32_e32 v31, v2
	v_mov_b32_e32 v32, v2
	v_mov_b32_e32 v33, v2
	v_mov_b32_e32 v54, v2
	v_mov_b32_e32 v55, v2
	v_mov_b32_e32 v56, v2
	v_mov_b32_e32 v57, v2
	v_mov_b32_e32 v62, v2
	v_mov_b32_e32 v63, v2
	v_mov_b32_e32 v64, v2
	v_mov_b32_e32 v65, v2
	v_mov_b32_e32 v86, v2
	v_mov_b32_e32 v87, v2
	v_mov_b32_e32 v88, v2
	v_mov_b32_e32 v89, v2
	v_mov_b32_e32 v94, v2
	v_mov_b32_e32 v95, v2
	v_mov_b32_e32 v96, v2
	v_mov_b32_e32 v97, v2
	v_mov_b32_e32 v118, v2
	v_mov_b32_e32 v119, v2
	v_mov_b32_e32 v120, v2
	v_mov_b32_e32 v121, v2
	v_mov_b32_e32 v126, v2
	v_mov_b32_e32 v127, v2
	v_mov_b32_e32 v128, v2
	v_mov_b32_e32 v129, v2
	v_readfirstlane_b32 s0, v193
	s_lshr_b32 s0, s0, 8
	s_cmp_eq_u32 s0, 1
	s_cbranch_scc0 .Lnp_637
	s_setprio 3

; #define PG8_BAR __builtin_amdgcn_s_barrier()
;     __device__ bool next(int i, Unit& u) const { const int L = i * G + c; if (L >= 512) return false; u.pm = 0; u.pn = L; u.offA = 0; u.offB = (size_t)L * 256 * 256 * 2; return true; }
; template <class Epi, class Sched>
; __device__ __forceinline__ void gemm_phase(LAS unsigned char* lds, const Gemm g, const Sched& S, const Epi& E) {
;     ...
;         const bool has_next = S.next(ui + 1, nxt);
;         const char* nA = has_next ? (const char*)g.A + nxt.offA : cA; const char* nB = has_next ? (const char*)g.Bt + nxt.offB : cB;
;         for (int t = 0; t < nt; t += 2) {
;             const bool last = (t == nt - 2);
;             const char* a1 = cA + (size_t)(t + 1) * kstep;
;             const char* a2 = last ? nA : cA + (size_t)(t + 2) * kstep; const char* b2 = last ? nB : cB + (size_t)(t + 2) * kstep;
;             const char* a3 = a2 + kstep; const char* b3 = b2 + kstep;
;     ...
;         if (!has_next) break;
; #pragma unroll
;         for (int a = 0; a < 2; ++a)
; #pragma unroll
;             for (int b = 0; b < 2; ++b)
; #pragma unroll
;                 for (int m = 0; m < 4; ++m)
; #pragma unroll
;                     for (int n = 0; n < 2; ++n) acc[a][b][m][n] = (f32x4){0.f, 0.f, 0.f, 0.f};
;         cur = nxt; cA = nA; cB = nB; ++ui;
;         if (wr == 1) PG8_BAR;
.LBB0_658:
	s_add_u32 s8, s2, s50
	s_addc_u32 s9, s3, s51
	v_readlane_b32 s0, v254, 4
	v_readlane_b32 s1, v254, 5
	s_add_u32 s20, s0, s76
	s_addc_u32 s21, s1, s77
	s_andn2_b64 vcc, exec, s[34:35]
	s_cbranch_vccnz .Lzc_19087
	s_and_b64 s[0:1], s[38:39], exec
	s_cselect_b32 s47, s9, s37
	s_cselect_b32 s49, s8, s36
	s_cselect_b32 s83, s21, s41
	s_cselect_b32 vcc_lo, s20, s40
	s_add_u32 s36, s36, 0x40080
	s_addc_u32 s37, s37, 0
	s_add_u32 vcc_hi, s40, 0x100
	v_mov_b32_e32 v6, 0
	s_addc_u32 s96, s41, 0
	s_mov_b32 s40, 0
	v_mov_b32_e32 v7, v6
	v_mov_b32_e32 v8, v6
	v_mov_b32_e32 v9, v6
	v_mov_b32_e32 v14, v6
	v_mov_b32_e32 v15, v6
	v_mov_b32_e32 v16, v6
	v_mov_b32_e32 v17, v6
	v_mov_b32_e32 v22, v6
	v_mov_b32_e32 v23, v6
	v_mov_b32_e32 v24, v6
	v_mov_b32_e32 v25, v6
	v_mov_b32_e32 v26, v6
	v_mov_b32_e32 v27, v6
	v_mov_b32_e32 v28, v6
	v_mov_b32_e32 v29, v6
	v_mov_b32_e32 v38, v6
	v_mov_b32_e32 v39, v6
	v_mov_b32_e32 v40, v6
	v_mov_b32_e32 v41, v6
	v_mov_b32_e32 v42, v6
	v_mov_b32_e32 v43, v6
	v_mov_b32_e32 v44, v6
	v_mov_b32_e32 v45, v6
	v_mov_b32_e32 v54, v6
	v_mov_b32_e32 v55, v6
	v_mov_b32_e32 v56, v6
	v_mov_b32_e32 v57, v6
	v_mov_b32_e32 v58, v6
	v_mov_b32_e32 v59, v6
	v_mov_b32_e32 v60, v6
	v_mov_b32_e32 v61, v6
	v_mov_b32_e32 v2, v6
	v_mov_b32_e32 v3, v6
	v_mov_b32_e32 v4, v6
	v_mov_b32_e32 v5, v6
	v_mov_b32_e32 v10, v6
	v_mov_b32_e32 v11, v6
	v_mov_b32_e32 v12, v6
	v_mov_b32_e32 v13, v6
	v_mov_b32_e32 v18, v6
	v_mov_b32_e32 v19, v6
	v_mov_b32_e32 v20, v6
	v_mov_b32_e32 v21, v6
	v_mov_b32_e32 v30, v6
	v_mov_b32_e32 v31, v6
	v_mov_b32_e32 v32, v6
	v_mov_b32_e32 v33, v6
	v_mov_b32_e32 v34, v6
	v_mov_b32_e32 v35, v6
	v_mov_b32_e32 v36, v6
	v_mov_b32_e32 v37, v6
	v_mov_b32_e32 v46, v6
	v_mov_b32_e32 v47, v6
	v_mov_b32_e32 v48, v6
	v_mov_b32_e32 v49, v6
	v_mov_b32_e32 v50, v6
	v_mov_b32_e32 v51, v6
	v_mov_b32_e32 v52, v6
	v_mov_b32_e32 v53, v6
	v_mov_b32_e32 v62, v6
	v_mov_b32_e32 v63, v6
	v_mov_b32_e32 v64, v6
	v_mov_b32_e32 v65, v6
	v_mov_b32_e32 v70, v6
	v_mov_b32_e32 v71, v6
	v_mov_b32_e32 v72, v6
	v_mov_b32_e32 v73, v6
	v_mov_b32_e32 v74, v6
	v_mov_b32_e32 v75, v6
	v_mov_b32_e32 v76, v6
	v_mov_b32_e32 v77, v6
	v_mov_b32_e32 v86, v6
	v_mov_b32_e32 v87, v6
	v_mov_b32_e32 v88, v6
	v_mov_b32_e32 v89, v6
	v_mov_b32_e32 v90, v6
	v_mov_b32_e32 v91, v6
	v_mov_b32_e32 v92, v6
	v_mov_b32_e32 v93, v6
	v_mov_b32_e32 v102, v6
	v_mov_b32_e32 v103, v6
	v_mov_b32_e32 v104, v6
	v_mov_b32_e32 v105, v6
	v_mov_b32_e32 v106, v6
	v_mov_b32_e32 v107, v6
	v_mov_b32_e32 v108, v6
	v_mov_b32_e32 v109, v6
	v_mov_b32_e32 v118, v6
	v_mov_b32_e32 v119, v6
	v_mov_b32_e32 v120, v6
	v_mov_b32_e32 v121, v6
	v_mov_b32_e32 v126, v6
	v_mov_b32_e32 v127, v6
	v_mov_b32_e32 v128, v6
	v_mov_b32_e32 v129, v6
	v_mov_b32_e32 v66, v6
	v_mov_b32_e32 v67, v6
	v_mov_b32_e32 v68, v6
	v_mov_b32_e32 v69, v6
	v_mov_b32_e32 v78, v6
	v_mov_b32_e32 v79, v6
	v_mov_b32_e32 v80, v6
	v_mov_b32_e32 v81, v6
	v_mov_b32_e32 v82, v6
	v_mov_b32_e32 v83, v6
	v_mov_b32_e32 v84, v6
	v_mov_b32_e32 v85, v6
	v_mov_b32_e32 v94, v6
	v_mov_b32_e32 v95, v6
	v_mov_b32_e32 v96, v6
	v_mov_b32_e32 v97, v6
	v_mov_b32_e32 v98, v6
	v_mov_b32_e32 v99, v6
	v_mov_b32_e32 v100, v6
	v_mov_b32_e32 v101, v6
	v_mov_b32_e32 v110, v6
	v_mov_b32_e32 v111, v6
	v_mov_b32_e32 v112, v6
	v_mov_b32_e32 v113, v6
	v_mov_b32_e32 v114, v6
	v_mov_b32_e32 v115, v6
	v_mov_b32_e32 v116, v6
	v_mov_b32_e32 v117, v6
	v_mov_b32_e32 v122, v6
	v_mov_b32_e32 v123, v6
	v_mov_b32_e32 v124, v6
	v_mov_b32_e32 v125, v6
	v_readfirstlane_b32 s0, v193
	s_lshr_b32 s0, s0, 8
	s_cmp_eq_u32 s0, 1
	s_cbranch_scc0 .Lnp_660
	s_setprio 3

; #define PG8_BAR __builtin_amdgcn_s_barrier()
;     __device__ bool next(int i, Unit& u) const { const int L = i * G + c; if (L >= 512) return false; u.pm = 0; u.pn = L; u.offA = 0; u.offB = (size_t)L * 256 * 256 * 2; return true; }
; template <class Epi, class Sched>
; __device__ __forceinline__ void gemm_phase(LAS unsigned char* lds, const Gemm g, const Sched& S, const Epi& E) {
;     ...
;         const bool has_next = S.next(ui + 1, nxt);
;         const char* nA = has_next ? (const char*)g.A + nxt.offA : cA; const char* nB = has_next ? (const char*)g.Bt + nxt.offB : cB;
;         for (int t = 0; t < nt; t += 2) {
;             const bool last = (t == nt - 2);
;             const char* a1 = cA + (size_t)(t + 1) * kstep;
;             const char* a2 = last ? nA : cA + (size_t)(t + 2) * kstep; const char* b2 = last ? nB : cB + (size_t)(t + 2) * kstep;
;             const char* a3 = a2 + kstep; const char* b3 = b2 + kstep;
;     ...
;         if (!has_next) break;
; #pragma unroll
;         for (int a = 0; a < 2; ++a)
; #pragma unroll
;             for (int b = 0; b < 2; ++b)
; #pragma unroll
;                 for (int m = 0; m < 4; ++m)
; #pragma unroll
;                     for (int n = 0; n < 2; ++n) acc[a][b][m][n] = (f32x4){0.f, 0.f, 0.f, 0.f};
;         cur = nxt; cA = nA; cB = nB; ++ui;
;         if (wr == 1) PG8_BAR;
.LBB0_761:
	s_add_u32 s40, s54, s36
	s_addc_u32 s41, s55, s37
	s_andn2_b64 vcc, exec, s[8:9]
	s_cbranch_vccnz .Lzc_21902
	s_and_b64 s[44:45], s[38:39], exec
	s_cselect_b32 s52, s41, s43
	s_cselect_b32 s56, s40, s42
	s_add_u32 s57, s42, 0x100
	v_mov_b32_e32 v2, 0
	v_readlane_b32 s22, v250, 4
	s_addc_u32 s64, s43, 0
	s_mov_b32 s46, 0
	s_mov_b64 s[42:43], 0
	v_mov_b32_e32 v3, v2
	v_mov_b32_e32 v4, v2
	v_mov_b32_e32 v5, v2
	v_mov_b32_e32 v6, v2
	v_mov_b32_e32 v7, v2
	v_mov_b32_e32 v8, v2
	v_mov_b32_e32 v9, v2
	v_mov_b32_e32 v18, v2
	v_mov_b32_e32 v19, v2
	v_mov_b32_e32 v20, v2
	v_mov_b32_e32 v21, v2
	v_mov_b32_e32 v22, v2
	v_mov_b32_e32 v23, v2
	v_mov_b32_e32 v24, v2
	v_mov_b32_e32 v25, v2
	v_mov_b32_e32 v34, v2
	v_mov_b32_e32 v35, v2
	v_mov_b32_e32 v36, v2
	v_mov_b32_e32 v37, v2
	v_mov_b32_e32 v38, v2
	v_mov_b32_e32 v39, v2
	v_mov_b32_e32 v40, v2
	v_mov_b32_e32 v41, v2
	v_mov_b32_e32 v50, v2
	v_mov_b32_e32 v51, v2
	v_mov_b32_e32 v52, v2
	v_mov_b32_e32 v53, v2
	v_mov_b32_e32 v54, v2
	v_mov_b32_e32 v55, v2
	v_mov_b32_e32 v56, v2
	v_mov_b32_e32 v57, v2
	v_mov_b32_e32 v10, v2
	v_mov_b32_e32 v11, v2
	v_mov_b32_e32 v12, v2
	v_mov_b32_e32 v13, v2
	v_mov_b32_e32 v14, v2
	v_mov_b32_e32 v15, v2
	v_mov_b32_e32 v16, v2
	v_mov_b32_e32 v17, v2
	v_mov_b32_e32 v26, v2
	v_mov_b32_e32 v27, v2
	v_mov_b32_e32 v28, v2
	v_mov_b32_e32 v29, v2
	v_mov_b32_e32 v30, v2
	v_mov_b32_e32 v31, v2
	v_mov_b32_e32 v32, v2
	v_mov_b32_e32 v33, v2
	v_mov_b32_e32 v42, v2
	v_mov_b32_e32 v43, v2
	v_mov_b32_e32 v44, v2
	v_mov_b32_e32 v45, v2
	v_mov_b32_e32 v46, v2
	v_mov_b32_e32 v47, v2
	v_mov_b32_e32 v48, v2
	v_mov_b32_e32 v49, v2
	v_mov_b32_e32 v58, v2
	v_mov_b32_e32 v59, v2
	v_mov_b32_e32 v60, v2
	v_mov_b32_e32 v61, v2
	v_mov_b32_e32 v62, v2
	v_mov_b32_e32 v63, v2
	v_mov_b32_e32 v64, v2
	v_mov_b32_e32 v65, v2
	v_mov_b32_e32 v66, v2
	v_mov_b32_e32 v67, v2
	v_mov_b32_e32 v68, v2
	v_mov_b32_e32 v69, v2
	v_mov_b32_e32 v70, v2
	v_mov_b32_e32 v71, v2
	v_mov_b32_e32 v72, v2
	v_mov_b32_e32 v73, v2
	v_mov_b32_e32 v82, v2
	v_mov_b32_e32 v83, v2
	v_mov_b32_e32 v84, v2
	v_mov_b32_e32 v85, v2
	v_mov_b32_e32 v86, v2
	v_mov_b32_e32 v87, v2
	v_mov_b32_e32 v88, v2
	v_mov_b32_e32 v89, v2
	v_mov_b32_e32 v98, v2
	v_mov_b32_e32 v99, v2
	v_mov_b32_e32 v100, v2
	v_mov_b32_e32 v101, v2
	v_mov_b32_e32 v102, v2
	v_mov_b32_e32 v103, v2
	v_mov_b32_e32 v104, v2
	v_mov_b32_e32 v105, v2
	v_mov_b32_e32 v114, v2
	v_mov_b32_e32 v115, v2
	v_mov_b32_e32 v116, v2
	v_mov_b32_e32 v117, v2
	v_mov_b32_e32 v118, v2
	v_mov_b32_e32 v119, v2
	v_mov_b32_e32 v120, v2
	v_mov_b32_e32 v121, v2
	v_mov_b32_e32 v74, v2
	v_mov_b32_e32 v75, v2
	v_mov_b32_e32 v76, v2
	v_mov_b32_e32 v77, v2
	v_mov_b32_e32 v78, v2
	v_mov_b32_e32 v79, v2
	v_mov_b32_e32 v80, v2
	v_mov_b32_e32 v81, v2
	v_mov_b32_e32 v90, v2
	v_mov_b32_e32 v91, v2
	v_mov_b32_e32 v92, v2
	v_mov_b32_e32 v93, v2
	v_mov_b32_e32 v94, v2
	v_mov_b32_e32 v95, v2
	v_mov_b32_e32 v96, v2
	v_mov_b32_e32 v97, v2
	v_mov_b32_e32 v106, v2
	v_mov_b32_e32 v107, v2
	v_mov_b32_e32 v108, v2
	v_mov_b32_e32 v109, v2
	v_mov_b32_e32 v110, v2
	v_mov_b32_e32 v111, v2
	v_mov_b32_e32 v112, v2
	v_mov_b32_e32 v113, v2
	v_mov_b32_e32 v126, v2
	v_mov_b32_e32 v127, v2
	v_mov_b32_e32 v128, v2
	v_mov_b32_e32 v129, v2
	v_mov_b32_e32 v122, v2
	v_mov_b32_e32 v123, v2
	v_mov_b32_e32 v124, v2
	v_mov_b32_e32 v125, v2
	v_readlane_b32 s23, v250, 5
	v_readlane_b32 s78, v250, 36
	v_readfirstlane_b32 s73, v193
	s_lshr_b32 s73, s73, 8
	s_cmp_eq_u32 s73, 1
	s_cbranch_scc0 .Lnp_763
	s_setprio 3

; #define PG8_BAR __builtin_amdgcn_s_barrier()
;     __device__ bool next(int i, Unit& u) const { const int L = i * G + c; if (L >= 512) return false; u.pm = 0; u.pn = L; u.offA = 0; u.offB = (size_t)L * 256 * 256 * 2; return true; }
; template <class Epi, class Sched>
; __device__ __forceinline__ void gemm_phase(LAS unsigned char* lds, const Gemm g, const Sched& S, const Epi& E) {
;     ...
;         const bool has_next = S.next(ui + 1, nxt);
;         const char* nA = has_next ? (const char*)g.A + nxt.offA : cA; const char* nB = has_next ? (const char*)g.Bt + nxt.offB : cB;
;         for (int t = 0; t < nt; t += 2) {
;             const bool last = (t == nt - 2);
;             const char* a1 = cA + (size_t)(t + 1) * kstep;
;             const char* a2 = last ? nA : cA + (size_t)(t + 2) * kstep; const char* b2 = last ? nB : cB + (size_t)(t + 2) * kstep;
;             const char* a3 = a2 + kstep; const char* b3 = b2 + kstep;
;     ...
;         if (!has_next) break;
; #pragma unroll
;         for (int a = 0; a < 2; ++a)
; #pragma unroll
;             for (int b = 0; b < 2; ++b)
; #pragma unroll
;                 for (int m = 0; m < 4; ++m)
; #pragma unroll
;                     for (int n = 0; n < 2; ++n) acc[a][b][m][n] = (f32x4){0.f, 0.f, 0.f, 0.f};
;         cur = nxt; cA = nA; cB = nB; ++ui;
;         if (wr == 1) PG8_BAR;
.LBB0_910:
	s_add_u32 s46, s54, s42
	s_addc_u32 s47, s55, s43
	v_readlane_b32 s22, v254, 12
	v_readlane_b32 s23, v254, 13
	s_add_u32 s48, s22, s44
	s_addc_u32 s49, s23, s45
	s_andn2_b64 vcc, exec, s[20:21]
	s_waitcnt lgkmcnt(0)
	s_cbranch_vccnz .Lzc_25928
	s_and_b64 s[76:77], s[36:37], exec
	s_cselect_b32 s39, s47, s1
	s_cselect_b32 s41, s46, s0
	s_cselect_b32 s82, s49, s51
	s_cselect_b32 s83, s48, s50
	s_add_u32 s0, s0, 0x40080
	s_addc_u32 s1, s1, 0
	s_add_u32 s84, s50, 0x100
	v_mov_b32_e32 v2, 0
	s_addc_u32 s85, s51, 0
	s_mov_b32 s50, 0
	v_mov_b32_e32 v3, v2
	v_mov_b32_e32 v4, v2
	v_mov_b32_e32 v5, v2
	v_mov_b32_e32 v6, v2
	v_mov_b32_e32 v7, v2
	v_mov_b32_e32 v8, v2
	v_mov_b32_e32 v9, v2
	v_mov_b32_e32 v18, v2
	v_mov_b32_e32 v19, v2
	v_mov_b32_e32 v20, v2
	v_mov_b32_e32 v21, v2
	v_mov_b32_e32 v22, v2
	v_mov_b32_e32 v23, v2
	v_mov_b32_e32 v24, v2
	v_mov_b32_e32 v25, v2
	v_mov_b32_e32 v34, v2
	v_mov_b32_e32 v35, v2
	v_mov_b32_e32 v36, v2
	v_mov_b32_e32 v37, v2
	v_mov_b32_e32 v38, v2
	v_mov_b32_e32 v39, v2
	v_mov_b32_e32 v40, v2
	v_mov_b32_e32 v41, v2
	v_mov_b32_e32 v50, v2
	v_mov_b32_e32 v51, v2
	v_mov_b32_e32 v52, v2
	v_mov_b32_e32 v53, v2
	v_mov_b32_e32 v54, v2
	v_mov_b32_e32 v55, v2
	v_mov_b32_e32 v56, v2
	v_mov_b32_e32 v57, v2
	v_mov_b32_e32 v10, v2
	v_mov_b32_e32 v11, v2
	v_mov_b32_e32 v12, v2
	v_mov_b32_e32 v13, v2
	v_mov_b32_e32 v14, v2
	v_mov_b32_e32 v15, v2
	v_mov_b32_e32 v16, v2
	v_mov_b32_e32 v17, v2
	v_mov_b32_e32 v26, v2
	v_mov_b32_e32 v27, v2
	v_mov_b32_e32 v28, v2
	v_mov_b32_e32 v29, v2
	v_mov_b32_e32 v30, v2
	v_mov_b32_e32 v31, v2
	v_mov_b32_e32 v32, v2
	v_mov_b32_e32 v33, v2
	v_mov_b32_e32 v42, v2
	v_mov_b32_e32 v43, v2
	v_mov_b32_e32 v44, v2
	v_mov_b32_e32 v45, v2
	v_mov_b32_e32 v46, v2
	v_mov_b32_e32 v47, v2
	v_mov_b32_e32 v48, v2
	v_mov_b32_e32 v49, v2
	v_mov_b32_e32 v58, v2
	v_mov_b32_e32 v59, v2
	v_mov_b32_e32 v60, v2
	v_mov_b32_e32 v61, v2
	v_mov_b32_e32 v62, v2
	v_mov_b32_e32 v63, v2
	v_mov_b32_e32 v64, v2
	v_mov_b32_e32 v65, v2
	v_mov_b32_e32 v66, v2
	v_mov_b32_e32 v67, v2
	v_mov_b32_e32 v68, v2
	v_mov_b32_e32 v69, v2
	v_mov_b32_e32 v70, v2
	v_mov_b32_e32 v71, v2
	v_mov_b32_e32 v72, v2
	v_mov_b32_e32 v73, v2
	v_mov_b32_e32 v82, v2
	v_mov_b32_e32 v83, v2
	v_mov_b32_e32 v84, v2
	v_mov_b32_e32 v85, v2
	v_mov_b32_e32 v86, v2
	v_mov_b32_e32 v87, v2
	v_mov_b32_e32 v88, v2
	v_mov_b32_e32 v89, v2
	v_mov_b32_e32 v98, v2
	v_mov_b32_e32 v99, v2
	v_mov_b32_e32 v100, v2
	v_mov_b32_e32 v101, v2
	v_mov_b32_e32 v102, v2
	v_mov_b32_e32 v103, v2
	v_mov_b32_e32 v104, v2
	v_mov_b32_e32 v105, v2
	v_mov_b32_e32 v114, v2
	v_mov_b32_e32 v115, v2
	v_mov_b32_e32 v116, v2
	v_mov_b32_e32 v117, v2
	v_mov_b32_e32 v118, v2
	v_mov_b32_e32 v119, v2
	v_mov_b32_e32 v120, v2
	v_mov_b32_e32 v121, v2
	v_mov_b32_e32 v74, v2
	v_mov_b32_e32 v75, v2
	v_mov_b32_e32 v76, v2
	v_mov_b32_e32 v77, v2
	v_mov_b32_e32 v78, v2
	v_mov_b32_e32 v79, v2
	v_mov_b32_e32 v80, v2
	v_mov_b32_e32 v81, v2
	v_mov_b32_e32 v90, v2
	v_mov_b32_e32 v91, v2
	v_mov_b32_e32 v92, v2
	v_mov_b32_e32 v93, v2
	v_mov_b32_e32 v94, v2
	v_mov_b32_e32 v95, v2
	v_mov_b32_e32 v96, v2
	v_mov_b32_e32 v97, v2
	v_mov_b32_e32 v106, v2
	v_mov_b32_e32 v107, v2
	v_mov_b32_e32 v108, v2
	v_mov_b32_e32 v109, v2
	v_mov_b32_e32 v110, v2
	v_mov_b32_e32 v111, v2
	v_mov_b32_e32 v112, v2
	v_mov_b32_e32 v113, v2
	v_mov_b32_e32 v126, v2
	v_mov_b32_e32 v127, v2
	v_mov_b32_e32 v128, v2
	v_mov_b32_e32 v129, v2
	v_mov_b32_e32 v122, v2
	v_mov_b32_e32 v123, v2
	v_mov_b32_e32 v124, v2
	v_mov_b32_e32 v125, v2
	v_readfirstlane_b32 s96, v193
	s_lshr_b32 s96, s96, 8
	s_cmp_eq_u32 s96, 1
	s_cbranch_scc0 .Lnp_912
	s_setprio 3
